# P3 chunk gate: LN-stat loads batched (32 in flight), bias load hoisted to group load batch
# baseline (speedup 1.0000x reference)
.LBB0_452:
	global_load_dwordx4 v[104:107], v[2:3], off offset:-32
	global_load_dwordx4 v[108:111], v[2:3], off offset:-16
	global_load_dwordx4 v[112:115], v[2:3], off
	global_load_dwordx4 v[116:119], v[2:3], off offset:16
	global_load_dwordx4 v[120:123], v[2:3], off offset:32
	global_load_dwordx4 v[124:127], v[2:3], off offset:48
	global_load_dwordx4 v[128:131], v[2:3], off offset:64
	global_load_dwordx4 v[132:135], v[2:3], off offset:80
	global_load_dwordx4 v[136:139], v[2:3], off offset:96
	global_load_dwordx4 v[140:143], v[2:3], off offset:112
	global_load_dwordx4 v[144:147], v[2:3], off offset:128
	global_load_dwordx4 v[148:151], v[2:3], off offset:144
	global_load_dwordx4 v[152:155], v[2:3], off offset:160
	global_load_dwordx4 v[156:159], v[2:3], off offset:176
	global_load_dwordx4 v[160:163], v[2:3], off offset:192
	global_load_dwordx4 v[164:167], v[2:3], off offset:208
	global_load_dwordx4 v[168:171], v[2:3], off offset:224
	global_load_dwordx4 v[172:175], v[2:3], off offset:240
	global_load_dwordx4 v[176:179], v[2:3], off offset:256
	global_load_dwordx4 v[180:183], v[2:3], off offset:272
	global_load_dwordx4 v[184:187], v[2:3], off offset:288
	global_load_dwordx4 v[188:191], v[2:3], off offset:304
	global_load_dwordx4 v[192:195], v[2:3], off offset:320
	global_load_dwordx4 v[196:199], v[2:3], off offset:336
	global_load_dwordx4 v[200:203], v[2:3], off offset:352
	global_load_dwordx4 v[204:207], v[2:3], off offset:368
	global_load_dwordx4 v[210:213], v[2:3], off offset:384
	global_load_dwordx4 v[214:217], v[2:3], off offset:400
	global_load_dwordx4 v[218:221], v[2:3], off offset:416
	global_load_dwordx4 v[222:225], v[2:3], off offset:432
	global_load_dwordx4 v[226:229], v[2:3], off offset:448
	global_load_dwordx4 v[230:233], v[2:3], off offset:464
	s_waitcnt vmcnt(31)
	v_lshlrev_b32_e32 v25, 16, v104
	v_and_b32_e32 v27, 0xffff0000, v104
	v_lshlrev_b32_e32 v29, 16, v105
	v_and_b32_e32 v105, 0xffff0000, v105
	v_mul_f32_e32 v24, v25, v25
	v_mul_f32_e32 v26, v27, v27
	v_lshlrev_b32_e32 v31, 16, v106
	v_and_b32_e32 v35, 0xffff0000, v106
	v_mul_f32_e32 v28, v29, v29
	v_mul_f32_e32 v104, v105, v105
	v_pk_add_f32 v[24:25], v[24:25], v[26:27]
	v_lshlrev_b32_e32 v37, 16, v107
	v_and_b32_e32 v107, 0xffff0000, v107
	v_mul_f32_e32 v30, v31, v31
	v_mul_f32_e32 v34, v35, v35
	v_pk_add_f32 v[104:105], v[28:29], v[104:105]
	v_pk_add_f32 v[4:5], v[4:5], v[24:25]
	s_waitcnt vmcnt(30)
	v_lshlrev_b32_e32 v39, 16, v108
	v_and_b32_e32 v41, 0xffff0000, v108
	v_mul_f32_e32 v36, v37, v37
	v_mul_f32_e32 v106, v107, v107
	v_pk_add_f32 v[26:27], v[30:31], v[34:35]
	v_pk_add_f32 v[4:5], v[104:105], v[4:5]
	v_lshlrev_b32_e32 v43, 16, v109
	v_and_b32_e32 v109, 0xffff0000, v109
	v_mul_f32_e32 v38, v39, v39
	v_mul_f32_e32 v40, v41, v41
	v_pk_add_f32 v[106:107], v[36:37], v[106:107]
	v_pk_add_f32 v[4:5], v[26:27], v[4:5]
	v_lshlrev_b32_e32 v45, 16, v110
	v_and_b32_e32 v47, 0xffff0000, v110
	v_mul_f32_e32 v42, v43, v43
	v_mul_f32_e32 v108, v109, v109
	v_pk_add_f32 v[28:29], v[38:39], v[40:41]
	v_pk_add_f32 v[4:5], v[106:107], v[4:5]
	v_lshlrev_b32_e32 v49, 16, v111
	v_and_b32_e32 v111, 0xffff0000, v111
	v_mul_f32_e32 v44, v45, v45
	v_mul_f32_e32 v46, v47, v47
	v_pk_add_f32 v[108:109], v[42:43], v[108:109]
	v_pk_add_f32 v[4:5], v[4:5], v[28:29]
	s_waitcnt vmcnt(29)
	v_lshlrev_b32_e32 v51, 16, v112
	v_and_b32_e32 v53, 0xffff0000, v112
	v_mul_f32_e32 v48, v49, v49
	v_mul_f32_e32 v110, v111, v111
	v_pk_add_f32 v[30:31], v[44:45], v[46:47]
	v_pk_add_f32 v[4:5], v[108:109], v[4:5]
	v_lshlrev_b32_e32 v55, 16, v113
	v_and_b32_e32 v113, 0xffff0000, v113
	v_mul_f32_e32 v50, v51, v51
	v_mul_f32_e32 v52, v53, v53
	v_pk_add_f32 v[110:111], v[48:49], v[110:111]
	v_pk_add_f32 v[4:5], v[30:31], v[4:5]
	v_lshlrev_b32_e32 v57, 16, v114
	v_and_b32_e32 v59, 0xffff0000, v114
	v_mul_f32_e32 v54, v55, v55
	v_mul_f32_e32 v112, v113, v113
	v_pk_add_f32 v[34:35], v[50:51], v[52:53]
	v_pk_add_f32 v[4:5], v[110:111], v[4:5]
	v_lshlrev_b32_e32 v61, 16, v115
	v_and_b32_e32 v115, 0xffff0000, v115
	v_mul_f32_e32 v56, v57, v57
	v_mul_f32_e32 v58, v59, v59
	v_pk_add_f32 v[112:113], v[54:55], v[112:113]
	v_pk_add_f32 v[4:5], v[4:5], v[34:35]
	s_waitcnt vmcnt(28)
	v_lshlrev_b32_e32 v63, 16, v116
	v_and_b32_e32 v65, 0xffff0000, v116
	v_mul_f32_e32 v60, v61, v61
	v_mul_f32_e32 v114, v115, v115
	v_pk_add_f32 v[36:37], v[56:57], v[58:59]
	v_pk_add_f32 v[4:5], v[112:113], v[4:5]
	v_lshlrev_b32_e32 v67, 16, v117
	v_and_b32_e32 v117, 0xffff0000, v117
	v_mul_f32_e32 v62, v63, v63
	v_mul_f32_e32 v64, v65, v65
	v_pk_add_f32 v[114:115], v[60:61], v[114:115]
	v_pk_add_f32 v[4:5], v[36:37], v[4:5]
	v_lshlrev_b32_e32 v69, 16, v118
	v_and_b32_e32 v71, 0xffff0000, v118
	v_mul_f32_e32 v66, v67, v67
	v_mul_f32_e32 v116, v117, v117
	v_pk_add_f32 v[38:39], v[62:63], v[64:65]
	v_pk_add_f32 v[4:5], v[114:115], v[4:5]
	v_lshlrev_b32_e32 v73, 16, v119
	v_and_b32_e32 v119, 0xffff0000, v119
	v_mul_f32_e32 v68, v69, v69
	v_mul_f32_e32 v70, v71, v71
	v_pk_add_f32 v[116:117], v[66:67], v[116:117]
	v_pk_add_f32 v[4:5], v[4:5], v[38:39]
	v_mul_f32_e32 v72, v73, v73
	v_mul_f32_e32 v118, v119, v119
	v_pk_add_f32 v[40:41], v[68:69], v[70:71]
	v_pk_add_f32 v[4:5], v[116:117], v[4:5]
	v_pk_add_f32 v[118:119], v[72:73], v[118:119]
	v_pk_add_f32 v[4:5], v[40:41], v[4:5]
	s_nop 0
	v_pk_add_f32 v[4:5], v[118:119], v[4:5]
	s_waitcnt vmcnt(27)
	v_lshlrev_b32_e32 v25, 16, v120
	v_and_b32_e32 v27, 0xffff0000, v120
	v_lshlrev_b32_e32 v29, 16, v121
	v_and_b32_e32 v121, 0xffff0000, v121
	v_mul_f32_e32 v24, v25, v25
	v_mul_f32_e32 v26, v27, v27
	v_lshlrev_b32_e32 v31, 16, v122
	v_and_b32_e32 v35, 0xffff0000, v122
	v_mul_f32_e32 v28, v29, v29
	v_mul_f32_e32 v120, v121, v121
	v_pk_add_f32 v[24:25], v[24:25], v[26:27]
	v_lshlrev_b32_e32 v37, 16, v123
	v_and_b32_e32 v123, 0xffff0000, v123
	v_mul_f32_e32 v30, v31, v31
	v_mul_f32_e32 v34, v35, v35
	v_pk_add_f32 v[120:121], v[28:29], v[120:121]
	v_pk_add_f32 v[4:5], v[4:5], v[24:25]
	s_waitcnt vmcnt(26)
	v_lshlrev_b32_e32 v39, 16, v124
	v_and_b32_e32 v41, 0xffff0000, v124
	v_mul_f32_e32 v36, v37, v37
	v_mul_f32_e32 v122, v123, v123
	v_pk_add_f32 v[26:27], v[30:31], v[34:35]
	v_pk_add_f32 v[4:5], v[120:121], v[4:5]
	v_lshlrev_b32_e32 v43, 16, v125
	v_and_b32_e32 v125, 0xffff0000, v125
	v_mul_f32_e32 v38, v39, v39
	v_mul_f32_e32 v40, v41, v41
	v_pk_add_f32 v[122:123], v[36:37], v[122:123]
	v_pk_add_f32 v[4:5], v[26:27], v[4:5]
	v_lshlrev_b32_e32 v45, 16, v126
	v_and_b32_e32 v47, 0xffff0000, v126
	v_mul_f32_e32 v42, v43, v43
	v_mul_f32_e32 v124, v125, v125
	v_pk_add_f32 v[28:29], v[38:39], v[40:41]
	v_pk_add_f32 v[4:5], v[122:123], v[4:5]
	v_lshlrev_b32_e32 v49, 16, v127
	v_and_b32_e32 v127, 0xffff0000, v127
	v_mul_f32_e32 v44, v45, v45
	v_mul_f32_e32 v46, v47, v47
	v_pk_add_f32 v[124:125], v[42:43], v[124:125]
	v_pk_add_f32 v[4:5], v[4:5], v[28:29]
	s_waitcnt vmcnt(25)
	v_lshlrev_b32_e32 v51, 16, v128
	v_and_b32_e32 v53, 0xffff0000, v128
	v_mul_f32_e32 v48, v49, v49
	v_mul_f32_e32 v126, v127, v127
	v_pk_add_f32 v[30:31], v[44:45], v[46:47]
	v_pk_add_f32 v[4:5], v[124:125], v[4:5]
	v_lshlrev_b32_e32 v55, 16, v129
	v_and_b32_e32 v129, 0xffff0000, v129
	v_mul_f32_e32 v50, v51, v51
	v_mul_f32_e32 v52, v53, v53
	v_pk_add_f32 v[126:127], v[48:49], v[126:127]
	v_pk_add_f32 v[4:5], v[30:31], v[4:5]
	v_lshlrev_b32_e32 v57, 16, v130
	v_and_b32_e32 v59, 0xffff0000, v130
	v_mul_f32_e32 v54, v55, v55
	v_mul_f32_e32 v128, v129, v129
	v_pk_add_f32 v[34:35], v[50:51], v[52:53]
	v_pk_add_f32 v[4:5], v[126:127], v[4:5]
	v_lshlrev_b32_e32 v61, 16, v131
	v_and_b32_e32 v131, 0xffff0000, v131
	v_mul_f32_e32 v56, v57, v57
	v_mul_f32_e32 v58, v59, v59
	v_pk_add_f32 v[128:129], v[54:55], v[128:129]
	v_pk_add_f32 v[4:5], v[4:5], v[34:35]
	s_waitcnt vmcnt(24)
	v_lshlrev_b32_e32 v63, 16, v132
	v_and_b32_e32 v65, 0xffff0000, v132
	v_mul_f32_e32 v60, v61, v61
	v_mul_f32_e32 v130, v131, v131
	v_pk_add_f32 v[36:37], v[56:57], v[58:59]
	v_pk_add_f32 v[4:5], v[128:129], v[4:5]
	v_lshlrev_b32_e32 v67, 16, v133
	v_and_b32_e32 v133, 0xffff0000, v133
	v_mul_f32_e32 v62, v63, v63
	v_mul_f32_e32 v64, v65, v65
	v_pk_add_f32 v[130:131], v[60:61], v[130:131]
	v_pk_add_f32 v[4:5], v[36:37], v[4:5]
	v_lshlrev_b32_e32 v69, 16, v134
	v_and_b32_e32 v71, 0xffff0000, v134
	v_mul_f32_e32 v66, v67, v67
	v_mul_f32_e32 v132, v133, v133
	v_pk_add_f32 v[38:39], v[62:63], v[64:65]
	v_pk_add_f32 v[4:5], v[130:131], v[4:5]
	v_lshlrev_b32_e32 v73, 16, v135
	v_and_b32_e32 v135, 0xffff0000, v135
	v_mul_f32_e32 v68, v69, v69
	v_mul_f32_e32 v70, v71, v71
	v_pk_add_f32 v[132:133], v[66:67], v[132:133]
	v_pk_add_f32 v[4:5], v[4:5], v[38:39]
	v_mul_f32_e32 v72, v73, v73
	v_mul_f32_e32 v134, v135, v135
	v_pk_add_f32 v[40:41], v[68:69], v[70:71]
	v_pk_add_f32 v[4:5], v[132:133], v[4:5]
	v_pk_add_f32 v[134:135], v[72:73], v[134:135]
	v_pk_add_f32 v[4:5], v[40:41], v[4:5]
	s_nop 0
	v_pk_add_f32 v[4:5], v[134:135], v[4:5]
	s_waitcnt vmcnt(23)
	v_lshlrev_b32_e32 v25, 16, v136
	v_and_b32_e32 v27, 0xffff0000, v136
	v_lshlrev_b32_e32 v29, 16, v137
	v_and_b32_e32 v137, 0xffff0000, v137
	v_mul_f32_e32 v24, v25, v25
	v_mul_f32_e32 v26, v27, v27
	v_lshlrev_b32_e32 v31, 16, v138
	v_and_b32_e32 v35, 0xffff0000, v138
	v_mul_f32_e32 v28, v29, v29
	v_mul_f32_e32 v136, v137, v137
	v_pk_add_f32 v[24:25], v[24:25], v[26:27]
	v_lshlrev_b32_e32 v37, 16, v139
	v_and_b32_e32 v139, 0xffff0000, v139
	v_mul_f32_e32 v30, v31, v31
	v_mul_f32_e32 v34, v35, v35
	v_pk_add_f32 v[136:137], v[28:29], v[136:137]
	v_pk_add_f32 v[4:5], v[4:5], v[24:25]
	s_waitcnt vmcnt(22)
	v_lshlrev_b32_e32 v39, 16, v140
	v_and_b32_e32 v41, 0xffff0000, v140
	v_mul_f32_e32 v36, v37, v37
	v_mul_f32_e32 v138, v139, v139
	v_pk_add_f32 v[26:27], v[30:31], v[34:35]
	v_pk_add_f32 v[4:5], v[136:137], v[4:5]
	v_lshlrev_b32_e32 v43, 16, v141
	v_and_b32_e32 v141, 0xffff0000, v141
	v_mul_f32_e32 v38, v39, v39
	v_mul_f32_e32 v40, v41, v41
	v_pk_add_f32 v[138:139], v[36:37], v[138:139]
	v_pk_add_f32 v[4:5], v[26:27], v[4:5]
	v_lshlrev_b32_e32 v45, 16, v142
	v_and_b32_e32 v47, 0xffff0000, v142
	v_mul_f32_e32 v42, v43, v43
	v_mul_f32_e32 v140, v141, v141
	v_pk_add_f32 v[28:29], v[38:39], v[40:41]
	v_pk_add_f32 v[4:5], v[138:139], v[4:5]
	v_lshlrev_b32_e32 v49, 16, v143
	v_and_b32_e32 v143, 0xffff0000, v143
	v_mul_f32_e32 v44, v45, v45
	v_mul_f32_e32 v46, v47, v47
	v_pk_add_f32 v[140:141], v[42:43], v[140:141]
	v_pk_add_f32 v[4:5], v[4:5], v[28:29]
	s_waitcnt vmcnt(21)
	v_lshlrev_b32_e32 v51, 16, v144
	v_and_b32_e32 v53, 0xffff0000, v144
	v_mul_f32_e32 v48, v49, v49
	v_mul_f32_e32 v142, v143, v143
	v_pk_add_f32 v[30:31], v[44:45], v[46:47]
	v_pk_add_f32 v[4:5], v[140:141], v[4:5]
	v_lshlrev_b32_e32 v55, 16, v145
	v_and_b32_e32 v145, 0xffff0000, v145
	v_mul_f32_e32 v50, v51, v51
	v_mul_f32_e32 v52, v53, v53
	v_pk_add_f32 v[142:143], v[48:49], v[142:143]
	v_pk_add_f32 v[4:5], v[30:31], v[4:5]
	v_lshlrev_b32_e32 v57, 16, v146
	v_and_b32_e32 v59, 0xffff0000, v146
	v_mul_f32_e32 v54, v55, v55
	v_mul_f32_e32 v144, v145, v145
	v_pk_add_f32 v[34:35], v[50:51], v[52:53]
	v_pk_add_f32 v[4:5], v[142:143], v[4:5]
	v_lshlrev_b32_e32 v61, 16, v147
	v_and_b32_e32 v147, 0xffff0000, v147
	v_mul_f32_e32 v56, v57, v57
	v_mul_f32_e32 v58, v59, v59
	v_pk_add_f32 v[144:145], v[54:55], v[144:145]
	v_pk_add_f32 v[4:5], v[4:5], v[34:35]
	s_waitcnt vmcnt(20)
	v_lshlrev_b32_e32 v63, 16, v148
	v_and_b32_e32 v65, 0xffff0000, v148
	v_mul_f32_e32 v60, v61, v61
	v_mul_f32_e32 v146, v147, v147
	v_pk_add_f32 v[36:37], v[56:57], v[58:59]
	v_pk_add_f32 v[4:5], v[144:145], v[4:5]
	v_lshlrev_b32_e32 v67, 16, v149
	v_and_b32_e32 v149, 0xffff0000, v149
	v_mul_f32_e32 v62, v63, v63
	v_mul_f32_e32 v64, v65, v65
	v_pk_add_f32 v[146:147], v[60:61], v[146:147]
	v_pk_add_f32 v[4:5], v[36:37], v[4:5]
	v_lshlrev_b32_e32 v69, 16, v150
	v_and_b32_e32 v71, 0xffff0000, v150
	v_mul_f32_e32 v66, v67, v67
	v_mul_f32_e32 v148, v149, v149
	v_pk_add_f32 v[38:39], v[62:63], v[64:65]
	v_pk_add_f32 v[4:5], v[146:147], v[4:5]
	v_lshlrev_b32_e32 v73, 16, v151
	v_and_b32_e32 v151, 0xffff0000, v151
	v_mul_f32_e32 v68, v69, v69
	v_mul_f32_e32 v70, v71, v71
	v_pk_add_f32 v[148:149], v[66:67], v[148:149]
	v_pk_add_f32 v[4:5], v[4:5], v[38:39]
	v_mul_f32_e32 v72, v73, v73
	v_mul_f32_e32 v150, v151, v151
	v_pk_add_f32 v[40:41], v[68:69], v[70:71]
	v_pk_add_f32 v[4:5], v[148:149], v[4:5]
	v_pk_add_f32 v[150:151], v[72:73], v[150:151]
	v_pk_add_f32 v[4:5], v[40:41], v[4:5]
	s_nop 0
	v_pk_add_f32 v[4:5], v[150:151], v[4:5]
	s_waitcnt vmcnt(19)
	v_lshlrev_b32_e32 v25, 16, v152
	v_and_b32_e32 v27, 0xffff0000, v152
	v_lshlrev_b32_e32 v29, 16, v153
	v_and_b32_e32 v153, 0xffff0000, v153
	v_mul_f32_e32 v24, v25, v25
	v_mul_f32_e32 v26, v27, v27
	v_lshlrev_b32_e32 v31, 16, v154
	v_and_b32_e32 v35, 0xffff0000, v154
	v_mul_f32_e32 v28, v29, v29
	v_mul_f32_e32 v152, v153, v153
	v_pk_add_f32 v[24:25], v[24:25], v[26:27]
	v_lshlrev_b32_e32 v37, 16, v155
	v_and_b32_e32 v155, 0xffff0000, v155
	v_mul_f32_e32 v30, v31, v31
	v_mul_f32_e32 v34, v35, v35
	v_pk_add_f32 v[152:153], v[28:29], v[152:153]
	v_pk_add_f32 v[4:5], v[4:5], v[24:25]
	s_waitcnt vmcnt(18)
	v_lshlrev_b32_e32 v39, 16, v156
	v_and_b32_e32 v41, 0xffff0000, v156
	v_mul_f32_e32 v36, v37, v37
	v_mul_f32_e32 v154, v155, v155
	v_pk_add_f32 v[26:27], v[30:31], v[34:35]
	v_pk_add_f32 v[4:5], v[152:153], v[4:5]
	v_lshlrev_b32_e32 v43, 16, v157
	v_and_b32_e32 v157, 0xffff0000, v157
	v_mul_f32_e32 v38, v39, v39
	v_mul_f32_e32 v40, v41, v41
	v_pk_add_f32 v[154:155], v[36:37], v[154:155]
	v_pk_add_f32 v[4:5], v[26:27], v[4:5]
	v_lshlrev_b32_e32 v45, 16, v158
	v_and_b32_e32 v47, 0xffff0000, v158
	v_mul_f32_e32 v42, v43, v43
	v_mul_f32_e32 v156, v157, v157
	v_pk_add_f32 v[28:29], v[38:39], v[40:41]
	v_pk_add_f32 v[4:5], v[154:155], v[4:5]
	v_lshlrev_b32_e32 v49, 16, v159
	v_and_b32_e32 v159, 0xffff0000, v159
	v_mul_f32_e32 v44, v45, v45
	v_mul_f32_e32 v46, v47, v47
	v_pk_add_f32 v[156:157], v[42:43], v[156:157]
	v_pk_add_f32 v[4:5], v[4:5], v[28:29]
	s_waitcnt vmcnt(17)
	v_lshlrev_b32_e32 v51, 16, v160
	v_and_b32_e32 v53, 0xffff0000, v160
	v_mul_f32_e32 v48, v49, v49
	v_mul_f32_e32 v158, v159, v159
	v_pk_add_f32 v[30:31], v[44:45], v[46:47]
	v_pk_add_f32 v[4:5], v[156:157], v[4:5]
	v_lshlrev_b32_e32 v55, 16, v161
	v_and_b32_e32 v161, 0xffff0000, v161
	v_mul_f32_e32 v50, v51, v51
	v_mul_f32_e32 v52, v53, v53
	v_pk_add_f32 v[158:159], v[48:49], v[158:159]
	v_pk_add_f32 v[4:5], v[30:31], v[4:5]
	v_lshlrev_b32_e32 v57, 16, v162
	v_and_b32_e32 v59, 0xffff0000, v162
	v_mul_f32_e32 v54, v55, v55
	v_mul_f32_e32 v160, v161, v161
	v_pk_add_f32 v[34:35], v[50:51], v[52:53]
	v_pk_add_f32 v[4:5], v[158:159], v[4:5]
	v_lshlrev_b32_e32 v61, 16, v163
	v_and_b32_e32 v163, 0xffff0000, v163
	v_mul_f32_e32 v56, v57, v57
	v_mul_f32_e32 v58, v59, v59
	v_pk_add_f32 v[160:161], v[54:55], v[160:161]
	v_pk_add_f32 v[4:5], v[4:5], v[34:35]
	s_waitcnt vmcnt(16)
	v_lshlrev_b32_e32 v63, 16, v164
	v_and_b32_e32 v65, 0xffff0000, v164
	v_mul_f32_e32 v60, v61, v61
	v_mul_f32_e32 v162, v163, v163
	v_pk_add_f32 v[36:37], v[56:57], v[58:59]
	v_pk_add_f32 v[4:5], v[160:161], v[4:5]
	v_lshlrev_b32_e32 v67, 16, v165
	v_and_b32_e32 v165, 0xffff0000, v165
	v_mul_f32_e32 v62, v63, v63
	v_mul_f32_e32 v64, v65, v65
	v_pk_add_f32 v[162:163], v[60:61], v[162:163]
	v_pk_add_f32 v[4:5], v[36:37], v[4:5]
	v_lshlrev_b32_e32 v69, 16, v166
	v_and_b32_e32 v71, 0xffff0000, v166
	v_mul_f32_e32 v66, v67, v67
	v_mul_f32_e32 v164, v165, v165
	v_pk_add_f32 v[38:39], v[62:63], v[64:65]
	v_pk_add_f32 v[4:5], v[162:163], v[4:5]
	v_lshlrev_b32_e32 v73, 16, v167
	v_and_b32_e32 v167, 0xffff0000, v167
	v_mul_f32_e32 v68, v69, v69
	v_mul_f32_e32 v70, v71, v71
	v_pk_add_f32 v[164:165], v[66:67], v[164:165]
	v_pk_add_f32 v[4:5], v[4:5], v[38:39]
	v_mul_f32_e32 v72, v73, v73
	v_mul_f32_e32 v166, v167, v167
	v_pk_add_f32 v[40:41], v[68:69], v[70:71]
	v_pk_add_f32 v[4:5], v[164:165], v[4:5]
	v_pk_add_f32 v[166:167], v[72:73], v[166:167]
	v_pk_add_f32 v[4:5], v[40:41], v[4:5]
	s_nop 0
	v_pk_add_f32 v[4:5], v[166:167], v[4:5]
	s_waitcnt vmcnt(15)
	v_lshlrev_b32_e32 v25, 16, v168
	v_and_b32_e32 v27, 0xffff0000, v168
	v_lshlrev_b32_e32 v29, 16, v169
	v_and_b32_e32 v169, 0xffff0000, v169
	v_mul_f32_e32 v24, v25, v25
	v_mul_f32_e32 v26, v27, v27
	v_lshlrev_b32_e32 v31, 16, v170
	v_and_b32_e32 v35, 0xffff0000, v170
	v_mul_f32_e32 v28, v29, v29
	v_mul_f32_e32 v168, v169, v169
	v_pk_add_f32 v[24:25], v[24:25], v[26:27]
	v_lshlrev_b32_e32 v37, 16, v171
	v_and_b32_e32 v171, 0xffff0000, v171
	v_mul_f32_e32 v30, v31, v31
	v_mul_f32_e32 v34, v35, v35
	v_pk_add_f32 v[168:169], v[28:29], v[168:169]
	v_pk_add_f32 v[4:5], v[4:5], v[24:25]
	s_waitcnt vmcnt(14)
	v_lshlrev_b32_e32 v39, 16, v172
	v_and_b32_e32 v41, 0xffff0000, v172
	v_mul_f32_e32 v36, v37, v37
	v_mul_f32_e32 v170, v171, v171
	v_pk_add_f32 v[26:27], v[30:31], v[34:35]
	v_pk_add_f32 v[4:5], v[168:169], v[4:5]
	v_lshlrev_b32_e32 v43, 16, v173
	v_and_b32_e32 v173, 0xffff0000, v173
	v_mul_f32_e32 v38, v39, v39
	v_mul_f32_e32 v40, v41, v41
	v_pk_add_f32 v[170:171], v[36:37], v[170:171]
	v_pk_add_f32 v[4:5], v[26:27], v[4:5]
	v_lshlrev_b32_e32 v45, 16, v174
	v_and_b32_e32 v47, 0xffff0000, v174
	v_mul_f32_e32 v42, v43, v43
	v_mul_f32_e32 v172, v173, v173
	v_pk_add_f32 v[28:29], v[38:39], v[40:41]
	v_pk_add_f32 v[4:5], v[170:171], v[4:5]
	v_lshlrev_b32_e32 v49, 16, v175
	v_and_b32_e32 v175, 0xffff0000, v175
	v_mul_f32_e32 v44, v45, v45
	v_mul_f32_e32 v46, v47, v47
	v_pk_add_f32 v[172:173], v[42:43], v[172:173]
	v_pk_add_f32 v[4:5], v[4:5], v[28:29]
	s_waitcnt vmcnt(13)
	v_lshlrev_b32_e32 v51, 16, v176
	v_and_b32_e32 v53, 0xffff0000, v176
	v_mul_f32_e32 v48, v49, v49
	v_mul_f32_e32 v174, v175, v175
	v_pk_add_f32 v[30:31], v[44:45], v[46:47]
	v_pk_add_f32 v[4:5], v[172:173], v[4:5]
	v_lshlrev_b32_e32 v55, 16, v177
	v_and_b32_e32 v177, 0xffff0000, v177
	v_mul_f32_e32 v50, v51, v51
	v_mul_f32_e32 v52, v53, v53
	v_pk_add_f32 v[174:175], v[48:49], v[174:175]
	v_pk_add_f32 v[4:5], v[30:31], v[4:5]
	v_lshlrev_b32_e32 v57, 16, v178
	v_and_b32_e32 v59, 0xffff0000, v178
	v_mul_f32_e32 v54, v55, v55
	v_mul_f32_e32 v176, v177, v177
	v_pk_add_f32 v[34:35], v[50:51], v[52:53]
	v_pk_add_f32 v[4:5], v[174:175], v[4:5]
	v_lshlrev_b32_e32 v61, 16, v179
	v_and_b32_e32 v179, 0xffff0000, v179
	v_mul_f32_e32 v56, v57, v57
	v_mul_f32_e32 v58, v59, v59
	v_pk_add_f32 v[176:177], v[54:55], v[176:177]
	v_pk_add_f32 v[4:5], v[4:5], v[34:35]
	s_waitcnt vmcnt(12)
	v_lshlrev_b32_e32 v63, 16, v180
	v_and_b32_e32 v65, 0xffff0000, v180
	v_mul_f32_e32 v60, v61, v61
	v_mul_f32_e32 v178, v179, v179
	v_pk_add_f32 v[36:37], v[56:57], v[58:59]
	v_pk_add_f32 v[4:5], v[176:177], v[4:5]
	v_lshlrev_b32_e32 v67, 16, v181
	v_and_b32_e32 v181, 0xffff0000, v181
	v_mul_f32_e32 v62, v63, v63
	v_mul_f32_e32 v64, v65, v65
	v_pk_add_f32 v[178:179], v[60:61], v[178:179]
	v_pk_add_f32 v[4:5], v[36:37], v[4:5]
	v_lshlrev_b32_e32 v69, 16, v182
	v_and_b32_e32 v71, 0xffff0000, v182
	v_mul_f32_e32 v66, v67, v67
	v_mul_f32_e32 v180, v181, v181
	v_pk_add_f32 v[38:39], v[62:63], v[64:65]
	v_pk_add_f32 v[4:5], v[178:179], v[4:5]
	v_lshlrev_b32_e32 v73, 16, v183
	v_and_b32_e32 v183, 0xffff0000, v183
	v_mul_f32_e32 v68, v69, v69
	v_mul_f32_e32 v70, v71, v71
	v_pk_add_f32 v[180:181], v[66:67], v[180:181]
	v_pk_add_f32 v[4:5], v[4:5], v[38:39]
	v_mul_f32_e32 v72, v73, v73
	v_mul_f32_e32 v182, v183, v183
	v_pk_add_f32 v[40:41], v[68:69], v[70:71]
	v_pk_add_f32 v[4:5], v[180:181], v[4:5]
	v_pk_add_f32 v[182:183], v[72:73], v[182:183]
	v_pk_add_f32 v[4:5], v[40:41], v[4:5]
	s_nop 0
	v_pk_add_f32 v[4:5], v[182:183], v[4:5]
	s_waitcnt vmcnt(11)
	v_lshlrev_b32_e32 v25, 16, v184
	v_and_b32_e32 v27, 0xffff0000, v184
	v_lshlrev_b32_e32 v29, 16, v185
	v_and_b32_e32 v185, 0xffff0000, v185
	v_mul_f32_e32 v24, v25, v25
	v_mul_f32_e32 v26, v27, v27
	v_lshlrev_b32_e32 v31, 16, v186
	v_and_b32_e32 v35, 0xffff0000, v186
	v_mul_f32_e32 v28, v29, v29
	v_mul_f32_e32 v184, v185, v185
	v_pk_add_f32 v[24:25], v[24:25], v[26:27]
	v_lshlrev_b32_e32 v37, 16, v187
	v_and_b32_e32 v187, 0xffff0000, v187
	v_mul_f32_e32 v30, v31, v31
	v_mul_f32_e32 v34, v35, v35
	v_pk_add_f32 v[184:185], v[28:29], v[184:185]
	v_pk_add_f32 v[4:5], v[4:5], v[24:25]
	s_waitcnt vmcnt(10)
	v_lshlrev_b32_e32 v39, 16, v188
	v_and_b32_e32 v41, 0xffff0000, v188
	v_mul_f32_e32 v36, v37, v37
	v_mul_f32_e32 v186, v187, v187
	v_pk_add_f32 v[26:27], v[30:31], v[34:35]
	v_pk_add_f32 v[4:5], v[184:185], v[4:5]
	v_lshlrev_b32_e32 v43, 16, v189
	v_and_b32_e32 v189, 0xffff0000, v189
	v_mul_f32_e32 v38, v39, v39
	v_mul_f32_e32 v40, v41, v41
	v_pk_add_f32 v[186:187], v[36:37], v[186:187]
	v_pk_add_f32 v[4:5], v[26:27], v[4:5]
	v_lshlrev_b32_e32 v45, 16, v190
	v_and_b32_e32 v47, 0xffff0000, v190
	v_mul_f32_e32 v42, v43, v43
	v_mul_f32_e32 v188, v189, v189
	v_pk_add_f32 v[28:29], v[38:39], v[40:41]
	v_pk_add_f32 v[4:5], v[186:187], v[4:5]
	v_lshlrev_b32_e32 v49, 16, v191
	v_and_b32_e32 v191, 0xffff0000, v191
	v_mul_f32_e32 v44, v45, v45
	v_mul_f32_e32 v46, v47, v47
	v_pk_add_f32 v[188:189], v[42:43], v[188:189]
	v_pk_add_f32 v[4:5], v[4:5], v[28:29]
	s_waitcnt vmcnt(9)
	v_lshlrev_b32_e32 v51, 16, v192
	v_and_b32_e32 v53, 0xffff0000, v192
	v_mul_f32_e32 v48, v49, v49
	v_mul_f32_e32 v190, v191, v191
	v_pk_add_f32 v[30:31], v[44:45], v[46:47]
	v_pk_add_f32 v[4:5], v[188:189], v[4:5]
	v_lshlrev_b32_e32 v55, 16, v193
	v_and_b32_e32 v193, 0xffff0000, v193
	v_mul_f32_e32 v50, v51, v51
	v_mul_f32_e32 v52, v53, v53
	v_pk_add_f32 v[190:191], v[48:49], v[190:191]
	v_pk_add_f32 v[4:5], v[30:31], v[4:5]
	v_lshlrev_b32_e32 v57, 16, v194
	v_and_b32_e32 v59, 0xffff0000, v194
	v_mul_f32_e32 v54, v55, v55
	v_mul_f32_e32 v192, v193, v193
	v_pk_add_f32 v[34:35], v[50:51], v[52:53]
	v_pk_add_f32 v[4:5], v[190:191], v[4:5]
	v_lshlrev_b32_e32 v61, 16, v195
	v_and_b32_e32 v195, 0xffff0000, v195
	v_mul_f32_e32 v56, v57, v57
	v_mul_f32_e32 v58, v59, v59
	v_pk_add_f32 v[192:193], v[54:55], v[192:193]
	v_pk_add_f32 v[4:5], v[4:5], v[34:35]
	s_waitcnt vmcnt(8)
	v_lshlrev_b32_e32 v63, 16, v196
	v_and_b32_e32 v65, 0xffff0000, v196
	v_mul_f32_e32 v60, v61, v61
	v_mul_f32_e32 v194, v195, v195
	v_pk_add_f32 v[36:37], v[56:57], v[58:59]
	v_pk_add_f32 v[4:5], v[192:193], v[4:5]
	v_lshlrev_b32_e32 v67, 16, v197
	v_and_b32_e32 v197, 0xffff0000, v197
	v_mul_f32_e32 v62, v63, v63
	v_mul_f32_e32 v64, v65, v65
	v_pk_add_f32 v[194:195], v[60:61], v[194:195]
	v_pk_add_f32 v[4:5], v[36:37], v[4:5]
	v_lshlrev_b32_e32 v69, 16, v198
	v_and_b32_e32 v71, 0xffff0000, v198
	v_mul_f32_e32 v66, v67, v67
	v_mul_f32_e32 v196, v197, v197
	v_pk_add_f32 v[38:39], v[62:63], v[64:65]
	v_pk_add_f32 v[4:5], v[194:195], v[4:5]
	v_lshlrev_b32_e32 v73, 16, v199
	v_and_b32_e32 v199, 0xffff0000, v199
	v_mul_f32_e32 v68, v69, v69
	v_mul_f32_e32 v70, v71, v71
	v_pk_add_f32 v[196:197], v[66:67], v[196:197]
	v_pk_add_f32 v[4:5], v[4:5], v[38:39]
	v_mul_f32_e32 v72, v73, v73
	v_mul_f32_e32 v198, v199, v199
	v_pk_add_f32 v[40:41], v[68:69], v[70:71]
	v_pk_add_f32 v[4:5], v[196:197], v[4:5]
	v_pk_add_f32 v[198:199], v[72:73], v[198:199]
	v_pk_add_f32 v[4:5], v[40:41], v[4:5]
	s_nop 0
	v_pk_add_f32 v[4:5], v[198:199], v[4:5]
	s_waitcnt vmcnt(7)
	v_lshlrev_b32_e32 v25, 16, v200
	v_and_b32_e32 v27, 0xffff0000, v200
	v_lshlrev_b32_e32 v29, 16, v201
	v_and_b32_e32 v201, 0xffff0000, v201
	v_mul_f32_e32 v24, v25, v25
	v_mul_f32_e32 v26, v27, v27
	v_lshlrev_b32_e32 v31, 16, v202
	v_and_b32_e32 v35, 0xffff0000, v202
	v_mul_f32_e32 v28, v29, v29
	v_mul_f32_e32 v200, v201, v201
	v_pk_add_f32 v[24:25], v[24:25], v[26:27]
	v_lshlrev_b32_e32 v37, 16, v203
	v_and_b32_e32 v203, 0xffff0000, v203
	v_mul_f32_e32 v30, v31, v31
	v_mul_f32_e32 v34, v35, v35
	v_pk_add_f32 v[200:201], v[28:29], v[200:201]
	v_pk_add_f32 v[4:5], v[4:5], v[24:25]
	s_waitcnt vmcnt(6)
	v_lshlrev_b32_e32 v39, 16, v204
	v_and_b32_e32 v41, 0xffff0000, v204
	v_mul_f32_e32 v36, v37, v37
	v_mul_f32_e32 v202, v203, v203
	v_pk_add_f32 v[26:27], v[30:31], v[34:35]
	v_pk_add_f32 v[4:5], v[200:201], v[4:5]
	v_lshlrev_b32_e32 v43, 16, v205
	v_and_b32_e32 v205, 0xffff0000, v205
	v_mul_f32_e32 v38, v39, v39
	v_mul_f32_e32 v40, v41, v41
	v_pk_add_f32 v[202:203], v[36:37], v[202:203]
	v_pk_add_f32 v[4:5], v[26:27], v[4:5]
	v_lshlrev_b32_e32 v45, 16, v206
	v_and_b32_e32 v47, 0xffff0000, v206
	v_mul_f32_e32 v42, v43, v43
	v_mul_f32_e32 v204, v205, v205
	v_pk_add_f32 v[28:29], v[38:39], v[40:41]
	v_pk_add_f32 v[4:5], v[202:203], v[4:5]
	v_lshlrev_b32_e32 v49, 16, v207
	v_and_b32_e32 v207, 0xffff0000, v207
	v_mul_f32_e32 v44, v45, v45
	v_mul_f32_e32 v46, v47, v47
	v_pk_add_f32 v[204:205], v[42:43], v[204:205]
	v_pk_add_f32 v[4:5], v[4:5], v[28:29]
	s_waitcnt vmcnt(5)
	v_lshlrev_b32_e32 v51, 16, v210
	v_and_b32_e32 v53, 0xffff0000, v210
	v_mul_f32_e32 v48, v49, v49
	v_mul_f32_e32 v206, v207, v207
	v_pk_add_f32 v[30:31], v[44:45], v[46:47]
	v_pk_add_f32 v[4:5], v[204:205], v[4:5]
	v_lshlrev_b32_e32 v55, 16, v211
	v_and_b32_e32 v211, 0xffff0000, v211
	v_mul_f32_e32 v50, v51, v51
	v_mul_f32_e32 v52, v53, v53
	v_pk_add_f32 v[206:207], v[48:49], v[206:207]
	v_pk_add_f32 v[4:5], v[30:31], v[4:5]
	v_lshlrev_b32_e32 v57, 16, v212
	v_and_b32_e32 v59, 0xffff0000, v212
	v_mul_f32_e32 v54, v55, v55
	v_mul_f32_e32 v210, v211, v211
	v_pk_add_f32 v[34:35], v[50:51], v[52:53]
	v_pk_add_f32 v[4:5], v[206:207], v[4:5]
	v_lshlrev_b32_e32 v61, 16, v213
	v_and_b32_e32 v213, 0xffff0000, v213
	v_mul_f32_e32 v56, v57, v57
	v_mul_f32_e32 v58, v59, v59
	v_pk_add_f32 v[210:211], v[54:55], v[210:211]
	v_pk_add_f32 v[4:5], v[4:5], v[34:35]
	s_waitcnt vmcnt(4)
	v_lshlrev_b32_e32 v63, 16, v214
	v_and_b32_e32 v65, 0xffff0000, v214
	v_mul_f32_e32 v60, v61, v61
	v_mul_f32_e32 v212, v213, v213
	v_pk_add_f32 v[36:37], v[56:57], v[58:59]
	v_pk_add_f32 v[4:5], v[210:211], v[4:5]
	v_lshlrev_b32_e32 v67, 16, v215
	v_and_b32_e32 v215, 0xffff0000, v215
	v_mul_f32_e32 v62, v63, v63
	v_mul_f32_e32 v64, v65, v65
	v_pk_add_f32 v[212:213], v[60:61], v[212:213]
	v_pk_add_f32 v[4:5], v[36:37], v[4:5]
	v_lshlrev_b32_e32 v69, 16, v216
	v_and_b32_e32 v71, 0xffff0000, v216
	v_mul_f32_e32 v66, v67, v67
	v_mul_f32_e32 v214, v215, v215
	v_pk_add_f32 v[38:39], v[62:63], v[64:65]
	v_pk_add_f32 v[4:5], v[212:213], v[4:5]
	v_lshlrev_b32_e32 v73, 16, v217
	v_and_b32_e32 v217, 0xffff0000, v217
	v_mul_f32_e32 v68, v69, v69
	v_mul_f32_e32 v70, v71, v71
	v_pk_add_f32 v[214:215], v[66:67], v[214:215]
	v_pk_add_f32 v[4:5], v[4:5], v[38:39]
	v_mul_f32_e32 v72, v73, v73
	v_mul_f32_e32 v216, v217, v217
	v_pk_add_f32 v[40:41], v[68:69], v[70:71]
	v_pk_add_f32 v[4:5], v[214:215], v[4:5]
	v_pk_add_f32 v[216:217], v[72:73], v[216:217]
	v_pk_add_f32 v[4:5], v[40:41], v[4:5]
	s_nop 0
	v_pk_add_f32 v[4:5], v[216:217], v[4:5]
	s_waitcnt vmcnt(3)
	v_lshlrev_b32_e32 v25, 16, v218
	v_and_b32_e32 v27, 0xffff0000, v218
	v_lshlrev_b32_e32 v29, 16, v219
	v_and_b32_e32 v219, 0xffff0000, v219
	v_mul_f32_e32 v24, v25, v25
	v_mul_f32_e32 v26, v27, v27
	v_lshlrev_b32_e32 v31, 16, v220
	v_and_b32_e32 v35, 0xffff0000, v220
	v_mul_f32_e32 v28, v29, v29
	v_mul_f32_e32 v218, v219, v219
	v_pk_add_f32 v[24:25], v[24:25], v[26:27]
	v_lshlrev_b32_e32 v37, 16, v221
	v_and_b32_e32 v221, 0xffff0000, v221
	v_mul_f32_e32 v30, v31, v31
	v_mul_f32_e32 v34, v35, v35
	v_pk_add_f32 v[218:219], v[28:29], v[218:219]
	v_pk_add_f32 v[4:5], v[4:5], v[24:25]
	s_waitcnt vmcnt(2)
	v_lshlrev_b32_e32 v39, 16, v222
	v_and_b32_e32 v41, 0xffff0000, v222
	v_mul_f32_e32 v36, v37, v37
	v_mul_f32_e32 v220, v221, v221
	v_pk_add_f32 v[26:27], v[30:31], v[34:35]
	v_pk_add_f32 v[4:5], v[218:219], v[4:5]
	v_lshlrev_b32_e32 v43, 16, v223
	v_and_b32_e32 v223, 0xffff0000, v223
	v_mul_f32_e32 v38, v39, v39
	v_mul_f32_e32 v40, v41, v41
	v_pk_add_f32 v[220:221], v[36:37], v[220:221]
	v_pk_add_f32 v[4:5], v[26:27], v[4:5]
	v_lshlrev_b32_e32 v45, 16, v224
	v_and_b32_e32 v47, 0xffff0000, v224
	v_mul_f32_e32 v42, v43, v43
	v_mul_f32_e32 v222, v223, v223
	v_pk_add_f32 v[28:29], v[38:39], v[40:41]
	v_pk_add_f32 v[4:5], v[220:221], v[4:5]
	v_lshlrev_b32_e32 v49, 16, v225
	v_and_b32_e32 v225, 0xffff0000, v225
	v_mul_f32_e32 v44, v45, v45
	v_mul_f32_e32 v46, v47, v47
	v_pk_add_f32 v[222:223], v[42:43], v[222:223]
	v_pk_add_f32 v[4:5], v[4:5], v[28:29]
	s_waitcnt vmcnt(1)
	v_lshlrev_b32_e32 v51, 16, v226
	v_and_b32_e32 v53, 0xffff0000, v226
	v_mul_f32_e32 v48, v49, v49
	v_mul_f32_e32 v224, v225, v225
	v_pk_add_f32 v[30:31], v[44:45], v[46:47]
	v_pk_add_f32 v[4:5], v[222:223], v[4:5]
	v_lshlrev_b32_e32 v55, 16, v227
	v_and_b32_e32 v227, 0xffff0000, v227
	v_mul_f32_e32 v50, v51, v51
	v_mul_f32_e32 v52, v53, v53
	v_pk_add_f32 v[224:225], v[48:49], v[224:225]
	v_pk_add_f32 v[4:5], v[30:31], v[4:5]
	v_lshlrev_b32_e32 v57, 16, v228
	v_and_b32_e32 v59, 0xffff0000, v228
	v_mul_f32_e32 v54, v55, v55
	v_mul_f32_e32 v226, v227, v227
	v_pk_add_f32 v[34:35], v[50:51], v[52:53]
	v_pk_add_f32 v[4:5], v[224:225], v[4:5]
	v_lshlrev_b32_e32 v61, 16, v229
	v_and_b32_e32 v229, 0xffff0000, v229
	v_mul_f32_e32 v56, v57, v57
	v_mul_f32_e32 v58, v59, v59
	v_pk_add_f32 v[226:227], v[54:55], v[226:227]
	v_pk_add_f32 v[4:5], v[4:5], v[34:35]
	s_waitcnt vmcnt(0)
	v_lshlrev_b32_e32 v63, 16, v230
	v_and_b32_e32 v65, 0xffff0000, v230
	v_mul_f32_e32 v60, v61, v61
	v_mul_f32_e32 v228, v229, v229
	v_pk_add_f32 v[36:37], v[56:57], v[58:59]
	v_pk_add_f32 v[4:5], v[226:227], v[4:5]
	v_lshlrev_b32_e32 v67, 16, v231
	v_and_b32_e32 v231, 0xffff0000, v231
	v_mul_f32_e32 v62, v63, v63
	v_mul_f32_e32 v64, v65, v65
	v_pk_add_f32 v[228:229], v[60:61], v[228:229]
	v_pk_add_f32 v[4:5], v[36:37], v[4:5]
	v_lshlrev_b32_e32 v69, 16, v232
	v_and_b32_e32 v71, 0xffff0000, v232
	v_mul_f32_e32 v66, v67, v67
	v_mul_f32_e32 v230, v231, v231
	v_pk_add_f32 v[38:39], v[62:63], v[64:65]
	v_pk_add_f32 v[4:5], v[228:229], v[4:5]
	v_lshlrev_b32_e32 v73, 16, v233
	v_and_b32_e32 v233, 0xffff0000, v233
	v_mul_f32_e32 v68, v69, v69
	v_mul_f32_e32 v70, v71, v71
	v_pk_add_f32 v[230:231], v[66:67], v[230:231]
	v_pk_add_f32 v[4:5], v[4:5], v[38:39]
	v_mul_f32_e32 v72, v73, v73
	v_mul_f32_e32 v232, v233, v233
	v_pk_add_f32 v[40:41], v[68:69], v[70:71]
	v_pk_add_f32 v[4:5], v[230:231], v[4:5]
	v_pk_add_f32 v[232:233], v[72:73], v[232:233]
	v_pk_add_f32 v[4:5], v[40:41], v[4:5]
	s_nop 0
	v_pk_add_f32 v[4:5], v[232:233], v[4:5]
	v_cmp_lt_i32_e32 vcc, v101, v102
	s_nop 1
	v_cndmask_b32_e32 v2, v100, v101, vcc
	v_lshlrev_b32_e32 v2, 2, v2
	ds_bpermute_b32 v3, v2, v5
	ds_bpermute_b32 v2, v2, v4
	v_cmp_lt_i32_e32 vcc, v103, v102
	s_waitcnt lgkmcnt(0)
	v_pk_add_f32 v[2:3], v[4:5], v[2:3]
	v_cndmask_b32_e32 v7, v100, v103, vcc
	v_lshlrev_b32_e32 v4, 2, v7
	ds_bpermute_b32 v5, v4, v3
	ds_bpermute_b32 v4, v4, v2
	v_cmp_eq_u32_e32 vcc, 0, v1
	s_and_saveexec_b64 s[26:27], vcc
	s_cbranch_execz .LBB0_455
	s_waitcnt lgkmcnt(0)
	v_pk_add_f32 v[2:3], v[2:3], v[4:5]
	s_nop 0
	v_pk_mul_f32 v[2:3], v[2:3], s[6:7] op_sel_hi:[1,0]
	s_nop 0
	v_fma_f32 v1, -v3, v3, v2
	v_max_f32_e32 v1, 0, v1
	v_add_f32_e32 v1, 0x358637bd, v1
	v_mul_f32_e32 v2, 0x4b800000, v1
	v_cmp_gt_f32_e32 vcc, s28, v1
	s_nop 1
	v_cndmask_b32_e32 v1, v1, v2, vcc
	v_rsq_f32_e32 v1, v1
	v_lshlrev_b32_e32 v2, 2, v0
	v_add_u32_e32 v4, 0x11000, v2
	ds_write_b32 v4, v3
	v_mul_f32_e32 v3, 0x45800000, v1
	v_cndmask_b32_e32 v1, v1, v3, vcc
	v_add_u32_e32 v2, 0x11200, v2
	ds_write_b32 v2, v1

.LBB0_456:
	v_lshl_add_u64 v[0:1], s[90:91], 0, v[64:65]
	v_lshl_add_u64 v[2:3], s[90:91], 0, v[60:61]
	v_lshl_add_u64 v[4:5], s[90:91], 0, v[56:57]
	v_lshl_add_u64 v[6:7], s[90:91], 0, v[52:53]
	v_lshl_add_u64 v[12:13], s[90:91], 0, v[44:45]
	v_lshl_add_u64 v[10:11], v[54:55], 0, s[20:21]
	v_lshl_add_u64 v[18:19], s[90:91], 0, v[46:47]
	v_lshl_add_u64 v[16:17], v[58:59], 0, s[20:21]
	v_lshl_add_u64 v[24:25], s[90:91], 0, v[48:49]
	v_lshl_add_u64 v[22:23], v[62:63], 0, s[20:21]
	v_lshl_add_u64 v[30:31], s[90:91], 0, v[50:51]
	v_lshl_add_u64 v[28:29], v[66:67], 0, s[20:21]
	v_lshl_add_u64 v[92:93], s[90:91], 0, v[80:81]
	v_lshl_add_u64 v[94:95], s[90:91], 0, v[76:77]
	v_lshl_add_u64 v[96:97], s[90:91], 0, v[72:73]
	v_lshl_add_u64 v[98:99], s[90:91], 0, v[68:69]
	v_lshl_add_u64 v[8:9], v[70:71], 0, s[20:21]
	v_lshl_add_u64 v[14:15], v[74:75], 0, s[20:21]
	v_lshl_add_u64 v[20:21], v[78:79], 0, s[20:21]
	v_lshl_add_u64 v[26:27], v[82:83], 0, s[20:21]
	v_lshl_add_u64 v[84:85], s[90:91], 0, v[42:43]
	v_lshl_add_u64 v[86:87], s[90:91], 0, v[40:41]
	v_lshl_add_u64 v[88:89], s[90:91], 0, v[38:39]
	v_lshl_add_u64 v[90:91], s[90:91], 0, v[36:37]
	global_load_dwordx4 v[118:121], v[0:1], off
	s_nop 0
	global_load_dwordx4 v[0:3], v[2:3], off
	s_nop 0
	global_load_dwordx4 v[122:125], v[4:5], off
	s_nop 0
	global_load_dwordx4 v[4:7], v[6:7], off
	s_nop 0
	global_load_dwordx4 v[126:129], v[12:13], off
	global_load_dwordx4 v[130:133], v[18:19], off
	global_load_dwordx4 v[134:137], v[24:25], off
	global_load_dwordx4 v[138:141], v[30:31], off
	global_load_dwordx4 v[142:145], v[10:11], off offset:16
	s_nop 0
	global_load_dwordx4 v[10:13], v[10:11], off
	s_nop 0
	global_load_dwordx4 v[146:149], v[8:9], off offset:16
	global_load_dwordx4 v[150:153], v[8:9], off
	global_load_dwordx4 v[154:157], v[16:17], off offset:16
	s_nop 0
	global_load_dwordx4 v[16:19], v[16:17], off
	s_nop 0
	global_load_dwordx4 v[158:161], v[14:15], off offset:16
	global_load_dwordx4 v[162:165], v[14:15], off
	global_load_dwordx4 v[166:169], v[22:23], off offset:16
	s_nop 0
	global_load_dwordx4 v[22:25], v[22:23], off
	s_nop 0
	global_load_dwordx4 v[170:173], v[20:21], off offset:16
	global_load_dwordx4 v[174:177], v[20:21], off
	global_load_dwordx4 v[178:181], v[28:29], off offset:16
	s_nop 0
	global_load_dwordx4 v[28:31], v[28:29], off
	s_nop 0
	global_load_dwordx4 v[182:185], v[26:27], off offset:16
	global_load_dwordx4 v[186:189], v[26:27], off
	global_load_dwordx4 v[190:193], v[92:93], off
	global_load_dwordx4 v[194:197], v[84:85], off
	s_nop 0
	global_load_dwordx4 v[92:95], v[94:95], off
	s_nop 0
	global_load_dwordx4 v[198:201], v[86:87], off
	global_load_dwordx4 v[202:205], v[96:97], off
	global_load_dwordx4 v[210:213], v[88:89], off
	s_nop 0
	global_load_dwordx4 v[96:99], v[98:99], off
	s_nop 0
	global_load_dwordx4 v[214:217], v[90:91], off
	v_ashrrev_i32_e32 v35, 31, v34
	v_lshl_add_u64 v[206:207], v[34:35], 2, s[80:81]
	global_load_dword v226, v[206:207], off
	s_add_u32 s20, s20, 0x200
	s_addc_u32 s21, s21, 0
	v_lshl_add_u64 v[36:37], v[36:37], 0, s[16:17]
	v_lshl_add_u64 v[38:39], v[38:39], 0, s[16:17]
	v_lshl_add_u64 v[40:41], v[40:41], 0, s[16:17]
	v_lshl_add_u64 v[42:43], v[42:43], 0, s[16:17]
	v_lshl_add_u64 v[44:45], v[44:45], 0, s[16:17]
	v_lshl_add_u64 v[46:47], v[46:47], 0, s[16:17]
	v_lshl_add_u64 v[48:49], v[48:49], 0, s[16:17]
	v_lshl_add_u64 v[50:51], v[50:51], 0, s[16:17]
	v_lshl_add_u64 v[52:53], v[52:53], 0, s[18:19]
	v_lshl_add_u64 v[56:57], v[56:57], 0, s[18:19]
	v_lshl_add_u64 v[60:61], v[60:61], 0, s[18:19]
	v_lshl_add_u64 v[64:65], v[64:65], 0, s[18:19]
	v_lshl_add_u64 v[68:69], v[68:69], 0, s[16:17]
	v_lshl_add_u64 v[72:73], v[72:73], 0, s[16:17]
	v_lshl_add_u64 v[76:77], v[76:77], 0, s[16:17]
	v_lshl_add_u64 v[80:81], v[80:81], 0, s[16:17]
	v_add_u32_e32 v34, 0x80, v34
	s_cmpk_lg_i32 s20, 0x1000
	s_waitcnt vmcnt(31)
	ds_write_b128 v32, v[118:121]
	s_waitcnt vmcnt(30)
	ds_write_b128 v107, v[0:3]
	s_waitcnt vmcnt(29)
	ds_write_b128 v108, v[122:125]
	s_waitcnt vmcnt(28)
	ds_write_b128 v109, v[4:7]
	s_waitcnt vmcnt(27)
	v_lshlrev_b32_e32 v0, 16, v126
	s_waitcnt vmcnt(26)
	v_lshlrev_b32_e32 v20, 16, v132
	v_and_b32_e32 v21, 0xffff0000, v132
	v_lshlrev_b32_e32 v26, 16, v133
	v_and_b32_e32 v27, 0xffff0000, v133
	ds_read_b32 v132, v104
	ds_read_b32 v133, v105
	v_and_b32_e32 v1, 0xffff0000, v126
	v_lshlrev_b32_e32 v2, 16, v127
	v_and_b32_e32 v3, 0xffff0000, v127
	v_lshlrev_b32_e32 v4, 16, v128
	v_and_b32_e32 v5, 0xffff0000, v128
	v_lshlrev_b32_e32 v6, 16, v129
	v_and_b32_e32 v7, 0xffff0000, v129
	v_lshlrev_b32_e32 v8, 16, v130
	v_and_b32_e32 v9, 0xffff0000, v130
	v_lshlrev_b32_e32 v14, 16, v131
	v_and_b32_e32 v15, 0xffff0000, v131
	s_waitcnt vmcnt(25)
	v_lshlrev_b32_e32 v35, 16, v134
	v_and_b32_e32 v117, 0xffff0000, v134
	v_and_b32_e32 v121, 0xffff0000, v136
	v_lshlrev_b32_e32 v122, 16, v137
	s_waitcnt vmcnt(24)
	v_lshlrev_b32_e32 v124, 16, v138
	v_and_b32_e32 v125, 0xffff0000, v138
	v_lshlrev_b32_e32 v126, 16, v139
	v_lshlrev_b32_e32 v128, 16, v140
	v_and_b32_e32 v129, 0xffff0000, v140
	v_lshlrev_b32_e32 v130, 16, v141
	v_lshlrev_b32_e32 v118, 16, v135
	v_and_b32_e32 v119, 0xffff0000, v135
	v_lshlrev_b32_e32 v120, 16, v136
	v_and_b32_e32 v123, 0xffff0000, v137
	v_and_b32_e32 v127, 0xffff0000, v139
	v_and_b32_e32 v131, 0xffff0000, v141
	s_waitcnt lgkmcnt(1)
	v_sub_f32_e32 v0, v0, v132
	v_sub_f32_e32 v1, v1, v132
	v_sub_f32_e32 v2, v2, v132
	v_sub_f32_e32 v3, v3, v132
	v_sub_f32_e32 v4, v4, v132
	v_sub_f32_e32 v5, v5, v132
	v_sub_f32_e32 v6, v6, v132
	v_sub_f32_e32 v7, v7, v132
	v_sub_f32_e32 v8, v8, v132
	v_sub_f32_e32 v9, v9, v132
	v_sub_f32_e32 v14, v14, v132
	v_sub_f32_e32 v15, v15, v132
	v_sub_f32_e32 v20, v20, v132
	v_sub_f32_e32 v21, v21, v132
	v_sub_f32_e32 v35, v35, v132
	v_sub_f32_e32 v117, v117, v132
	v_sub_f32_e32 v121, v121, v132
	v_sub_f32_e32 v122, v122, v132
	v_sub_f32_e32 v124, v124, v132
	v_sub_f32_e32 v125, v125, v132
	v_sub_f32_e32 v126, v126, v132
	v_sub_f32_e32 v128, v128, v132
	v_sub_f32_e32 v129, v129, v132
	v_sub_f32_e32 v130, v130, v132
	v_sub_f32_e32 v26, v26, v132
	v_sub_f32_e32 v27, v27, v132
	v_sub_f32_e32 v118, v118, v132
	v_sub_f32_e32 v119, v119, v132
	v_sub_f32_e32 v120, v120, v132
	v_sub_f32_e32 v123, v123, v132
	v_sub_f32_e32 v127, v127, v132
	v_sub_f32_e32 v131, v131, v132
	s_waitcnt lgkmcnt(0)
	v_mul_f32_e32 v0, v133, v0
	v_mul_f32_e32 v1, v133, v1
	v_mul_f32_e32 v2, v133, v2
	v_mul_f32_e32 v3, v133, v3
	v_mul_f32_e32 v4, v133, v4
	v_mul_f32_e32 v5, v133, v5
	v_mul_f32_e32 v6, v133, v6
	v_mul_f32_e32 v7, v133, v7
	v_mul_f32_e32 v8, v133, v8
	v_mul_f32_e32 v9, v133, v9
	v_mul_f32_e32 v14, v133, v14
	v_mul_f32_e32 v15, v133, v15
	v_mul_f32_e32 v20, v133, v20
	v_mul_f32_e32 v21, v133, v21
	v_mul_f32_e32 v35, v133, v35
	v_mul_f32_e32 v117, v133, v117
	v_mul_f32_e32 v121, v133, v121
	v_mul_f32_e32 v122, v133, v122
	v_mul_f32_e32 v124, v133, v124
	v_mul_f32_e32 v125, v133, v125
	v_mul_f32_e32 v126, v133, v126
	v_mul_f32_e32 v128, v133, v128
	v_mul_f32_e32 v129, v133, v129
	v_mul_f32_e32 v130, v133, v130
	v_mul_f32_e32 v26, v133, v26
	v_mul_f32_e32 v27, v133, v27
	v_mul_f32_e32 v118, v133, v118
	v_mul_f32_e32 v119, v133, v119
	v_mul_f32_e32 v120, v133, v120
	v_mul_f32_e32 v123, v133, v123
	v_mul_f32_e32 v127, v133, v127
	v_mul_f32_e32 v131, v133, v131
	s_waitcnt vmcnt(20)
	v_fma_f32 v0, v10, v0, v150
	v_fma_f32 v1, v11, v1, v151
	v_fma_f32 v2, v2, v12, v152
	v_fmac_f32_e32 v153, v3, v13
	v_fma_f32 v3, v4, v142, v146
	v_fma_f32 v4, v5, v143, v147
	v_fma_f32 v5, v6, v144, v148
	v_fmac_f32_e32 v149, v7, v145
	s_waitcnt vmcnt(16)
	v_fma_f32 v6, v16, v8, v162
	v_fma_f32 v7, v17, v9, v163
	v_fma_f32 v8, v14, v18, v164
	v_fmac_f32_e32 v165, v15, v19
	v_fma_f32 v9, v20, v154, v158
	v_fma_f32 v10, v21, v155, v159
	s_waitcnt vmcnt(12)
	v_fma_f32 v12, v22, v35, v174
	v_fma_f32 v13, v23, v117, v175
	v_fma_f32 v16, v121, v167, v171
	v_fma_f32 v17, v122, v168, v172
	s_waitcnt vmcnt(8)
	v_fma_f32 v18, v28, v124, v186
	v_fma_f32 v19, v29, v125, v187
	v_fma_f32 v20, v126, v30, v188
	v_fma_f32 v21, v128, v178, v182
	v_fma_f32 v22, v129, v179, v183
	v_fma_f32 v23, v130, v180, v184
	v_fma_f32 v11, v26, v156, v160
	v_fmac_f32_e32 v161, v27, v157
	v_fma_f32 v14, v118, v24, v176
	v_fmac_f32_e32 v177, v119, v25
	v_fma_f32 v15, v120, v166, v170
	v_fmac_f32_e32 v173, v123, v169
	v_fmac_f32_e32 v189, v127, v31
	v_fmac_f32_e32 v185, v131, v181
	v_cvt_pk_bf16_f32 v0, v0, s0
	v_cvt_pk_bf16_f32 v1, v1, s0
	v_cvt_pk_bf16_f32 v2, v2, s0
	v_cvt_pk_bf16_f32 v3, v3, s0
	v_cvt_pk_bf16_f32 v16, v16, s0
	v_cvt_pk_bf16_f32 v17, v17, s0
	v_cvt_pk_bf16_f32 v18, v18, s0
	v_cvt_pk_bf16_f32 v19, v19, s0
	v_cvt_pk_bf16_f32 v20, v20, s0
	v_cvt_pk_bf16_f32 v21, v21, s0
	v_cvt_pk_bf16_f32 v22, v22, s0
	v_cvt_pk_bf16_f32 v23, v23, s0
	v_cvt_pk_bf16_f32 v24, v153, s0
	v_cvt_pk_bf16_f32 v4, v4, s0
	v_cvt_pk_bf16_f32 v5, v5, s0
	v_cvt_pk_bf16_f32 v25, v149, s0
	v_cvt_pk_bf16_f32 v6, v6, s0
	v_cvt_pk_bf16_f32 v7, v7, s0
	v_cvt_pk_bf16_f32 v8, v8, s0
	v_cvt_pk_bf16_f32 v26, v165, s0
	v_cvt_pk_bf16_f32 v9, v9, s0
	v_cvt_pk_bf16_f32 v10, v10, s0
	v_cvt_pk_bf16_f32 v11, v11, s0
	v_cvt_pk_bf16_f32 v27, v161, s0
	v_cvt_pk_bf16_f32 v12, v12, s0
	v_cvt_pk_bf16_f32 v13, v13, s0
	v_cvt_pk_bf16_f32 v14, v14, s0
	v_cvt_pk_bf16_f32 v28, v177, s0
	v_cvt_pk_bf16_f32 v15, v15, s0
	v_cvt_pk_bf16_f32 v29, v173, s0
	v_cvt_pk_bf16_f32 v30, v189, s0
	v_cvt_pk_bf16_f32 v31, v185, s0
	ds_write_b16 v110, v0 offset:34816
	ds_write_b16 v110, v1 offset:35088
	ds_write_b16 v110, v2 offset:35360
	ds_write_b16 v110, v24 offset:35632
	ds_write_b16 v110, v3 offset:35904
	ds_write_b16 v110, v4 offset:36176
	ds_write_b16 v110, v5 offset:36448
	ds_write_b16 v110, v25 offset:36720
	ds_write_b16 v111, v6 offset:34816
	ds_write_b16 v111, v7 offset:35088
	ds_write_b16 v111, v8 offset:35360
	ds_write_b16 v111, v26 offset:35632
	ds_write_b16 v111, v9 offset:35904
	ds_write_b16 v111, v10 offset:36176
	ds_write_b16 v111, v11 offset:36448
	ds_write_b16 v111, v27 offset:36720
	ds_write_b16 v112, v12 offset:34816
	ds_write_b16 v112, v13 offset:35088
	ds_write_b16 v112, v14 offset:35360
	ds_write_b16 v112, v28 offset:35632
	ds_write_b16 v112, v15 offset:35904
	ds_write_b16 v112, v16 offset:36176
	ds_write_b16 v112, v17 offset:36448
	ds_write_b16 v112, v29 offset:36720
	ds_write_b16 v113, v18 offset:34816
	ds_write_b16 v113, v19 offset:35088
	ds_write_b16 v113, v20 offset:35360
	ds_write_b16 v113, v30 offset:35632
	ds_write_b16 v113, v21 offset:35904
	ds_write_b16 v113, v22 offset:36176
	ds_write_b16 v113, v23 offset:36448
	ds_write_b16 v113, v31 offset:36720
	s_waitcnt lgkmcnt(0)
	s_barrier
	ds_read_b128 v[0:3], v114 offset:34816
	ds_read_b128 v[16:19], v115
	ds_read_b128 v[118:121], v115 offset:32
	ds_read_b128 v[122:125], v114 offset:34848
	ds_read_b128 v[20:23], v114 offset:43520
	ds_read_b128 v[126:129], v114 offset:43552
	s_waitcnt lgkmcnt(4)
	v_mfma_f32_32x32x16_bf16 v[0:15], v[0:3], v[16:19], 0
	ds_read_b128 v[130:133], v115 offset:64
	ds_read_b128 v[134:137], v115 offset:96
	ds_read_b128 v[138:141], v114 offset:34880
	ds_read_b128 v[142:145], v114 offset:34912
	ds_read_b128 v[146:149], v114 offset:43584
	ds_read_b128 v[150:153], v114 offset:43616
	ds_read_b128 v[154:157], v115 offset:128
	ds_read_b128 v[158:161], v115 offset:160
	ds_read_b128 v[162:165], v114 offset:34944
	ds_read_b128 v[166:169], v114 offset:34976
	ds_read_b128 v[170:173], v114 offset:43648
	ds_read_b128 v[174:177], v114 offset:43680
	ds_read_b128 v[178:181], v115 offset:192
	ds_read_b128 v[182:185], v115 offset:224
	s_waitcnt lgkmcnt(14)
	v_mfma_f32_32x32x16_bf16 v[0:15], v[122:125], v[118:121], v[0:15]
	ds_read_b128 v[122:125], v114 offset:35008
	ds_read_b128 v[186:189], v114 offset:35040
	ds_read_b128 v[218:221], v114 offset:43712
	ds_read_b128 v[222:225], v114 offset:43744
	s_waitcnt lgkmcnt(0)
	s_barrier
	s_waitcnt vmcnt(7)
	ds_write_b128 v32, v[190:193]
	s_waitcnt vmcnt(6)
	ds_write_b128 v32, v[194:197] offset:34816
	s_waitcnt vmcnt(5)
	ds_write_b128 v107, v[92:95]
	s_waitcnt vmcnt(4)
	ds_write_b128 v107, v[198:201] offset:34816
	s_waitcnt vmcnt(3)
	ds_write_b128 v108, v[202:205]
	s_waitcnt vmcnt(2)
	ds_write_b128 v108, v[210:213] offset:34816
	s_waitcnt vmcnt(1)
	ds_write_b128 v109, v[96:99]
	s_waitcnt vmcnt(0)
	ds_write_b128 v109, v[214:217] offset:34816
	s_waitcnt lgkmcnt(0)
	s_barrier
	v_mfma_f32_32x32x16_bf16 v[16:31], v[20:23], v[16:19], 0
	ds_read2_b64 v[92:95], v116 offset1:2
	ds_read2_b64 v[96:99], v106 offset1:2
	s_waitcnt lgkmcnt(0)
	v_lshlrev_b32_e32 v196, 16, v96
	v_and_b32_e32 v197, 0xffff0000, v96
	v_mfma_f32_32x32x16_bf16 v[16:31], v[126:129], v[118:121], v[16:31]
	v_lshlrev_b32_e32 v96, 16, v97
	v_and_b32_e32 v97, 0xffff0000, v97
	v_mfma_f32_32x32x16_bf16 v[0:15], v[138:141], v[130:133], v[0:15]
	v_mfma_f32_32x32x16_bf16 v[16:31], v[146:149], v[130:133], v[16:31]
	ds_read2_b64 v[118:121], v106 offset0:4 offset1:6
	ds_read2_b64 v[126:129], v116 offset0:4 offset1:6
	ds_read2_b64 v[130:133], v106 offset0:8 offset1:10
	ds_read2_b64 v[138:141], v116 offset0:8 offset1:10
	ds_read2_b64 v[146:149], v106 offset0:12 offset1:14
	ds_read2_b64 v[190:193], v116 offset0:12 offset1:14
	v_mfma_f32_32x32x16_bf16 v[0:15], v[142:145], v[134:137], v[0:15]
	s_waitcnt lgkmcnt(5)
	v_lshlrev_b32_e32 v144, 16, v118
	v_and_b32_e32 v145, 0xffff0000, v118
	v_lshlrev_b32_e32 v118, 16, v119
	v_and_b32_e32 v119, 0xffff0000, v119
	v_lshlrev_b32_e32 v142, 16, v92
	v_and_b32_e32 v143, 0xffff0000, v92
	v_lshlrev_b32_e32 v92, 16, v93
	v_mfma_f32_32x32x16_bf16 v[16:31], v[150:153], v[134:137], v[16:31]
	v_lshlrev_b32_e32 v134, 16, v98
	v_and_b32_e32 v135, 0xffff0000, v98
	v_lshlrev_b32_e32 v98, 16, v99
	v_and_b32_e32 v99, 0xffff0000, v99
	v_lshlrev_b32_e32 v152, 16, v120
	v_and_b32_e32 v153, 0xffff0000, v120
	v_lshlrev_b32_e32 v120, 16, v121
	v_mfma_f32_32x32x16_bf16 v[0:15], v[162:165], v[154:157], v[0:15]
	v_and_b32_e32 v121, 0xffff0000, v121
	v_and_b32_e32 v93, 0xffff0000, v93
	v_lshlrev_b32_e32 v136, 16, v94
	v_and_b32_e32 v137, 0xffff0000, v94
	v_lshlrev_b32_e32 v94, 16, v95
	v_and_b32_e32 v95, 0xffff0000, v95
	s_waitcnt lgkmcnt(4)
	v_lshlrev_b32_e32 v150, 16, v126
	v_mfma_f32_32x32x16_bf16 v[16:31], v[170:173], v[154:157], v[16:31]
	s_waitcnt lgkmcnt(3)
	v_lshlrev_b32_e32 v156, 16, v130
	v_and_b32_e32 v157, 0xffff0000, v130
	v_lshlrev_b32_e32 v130, 16, v131
	v_and_b32_e32 v131, 0xffff0000, v131
	v_and_b32_e32 v151, 0xffff0000, v126
	v_lshlrev_b32_e32 v126, 16, v127
	v_and_b32_e32 v127, 0xffff0000, v127
	v_mfma_f32_32x32x16_bf16 v[0:15], v[166:169], v[158:161], v[0:15]
	s_waitcnt lgkmcnt(1)
	v_lshlrev_b32_e32 v166, 16, v148
	v_and_b32_e32 v167, 0xffff0000, v148
	v_lshlrev_b32_e32 v148, 16, v149
	v_and_b32_e32 v149, 0xffff0000, v149
	v_lshlrev_b32_e32 v154, 16, v128
	v_and_b32_e32 v155, 0xffff0000, v128
	v_lshlrev_b32_e32 v128, 16, v129
	v_mfma_f32_32x32x16_bf16 v[16:31], v[174:177], v[158:161], v[16:31]
	v_lshlrev_b32_e32 v158, 16, v132
	v_and_b32_e32 v159, 0xffff0000, v132
	v_lshlrev_b32_e32 v132, 16, v146
	v_and_b32_e32 v129, 0xffff0000, v129
	v_lshlrev_b32_e32 v162, 16, v138
	v_and_b32_e32 v163, 0xffff0000, v138
	v_lshlrev_b32_e32 v138, 16, v139
	v_mfma_f32_32x32x16_bf16 v[0:15], v[122:125], v[178:181], v[0:15]
	v_lshlrev_b32_e32 v122, 16, v133
	v_and_b32_e32 v123, 0xffff0000, v133
	v_and_b32_e32 v133, 0xffff0000, v146
	v_lshlrev_b32_e32 v146, 16, v147
	v_and_b32_e32 v147, 0xffff0000, v147
	v_and_b32_e32 v139, 0xffff0000, v139
	v_lshlrev_b32_e32 v160, 16, v140
	v_mfma_f32_32x32x16_bf16 v[16:31], v[218:221], v[178:181], v[16:31]
	v_and_b32_e32 v161, 0xffff0000, v140
	v_lshlrev_b32_e32 v124, 16, v141
	v_and_b32_e32 v125, 0xffff0000, v141
	s_waitcnt lgkmcnt(0)
	v_lshlrev_b32_e32 v140, 16, v190
	v_and_b32_e32 v141, 0xffff0000, v190
	v_lshlrev_b32_e32 v164, 16, v191
	v_and_b32_e32 v165, 0xffff0000, v191
	v_mfma_f32_32x32x16_bf16 v[0:15], v[186:189], v[182:185], v[0:15]
	v_lshlrev_b32_e32 v168, 16, v192
	v_and_b32_e32 v169, 0xffff0000, v192
	v_lshlrev_b32_e32 v170, 16, v193
	v_and_b32_e32 v171, 0xffff0000, v193
	v_mfma_f32_32x32x16_bf16 v[16:31], v[222:225], v[182:185], v[16:31]
	s_waitcnt vmcnt(0)
	s_nop 5
	v_add_f32_e64 v0, v0, v226
	v_add_f32_e64 v1, v1, v226
	v_add_f32_e64 v2, v2, v226
	v_add_f32_e64 v3, v3, v226
	v_pk_add_f32 v[4:5], v[4:5], v[226:227] op_sel_hi:[1,0]
	v_pk_add_f32 v[6:7], v[6:7], v[226:227] op_sel_hi:[1,0]
	v_pk_add_f32 v[8:9], v[8:9], v[226:227] op_sel_hi:[1,0]
	v_pk_add_f32 v[10:11], v[10:11], v[226:227] op_sel_hi:[1,0]
	v_pk_add_f32 v[12:13], v[12:13], v[226:227] op_sel_hi:[1,0]
	v_pk_add_f32 v[14:15], v[14:15], v[226:227] op_sel_hi:[1,0]
	v_pk_add_f32 v[16:17], v[16:17], v[226:227] op_sel_hi:[1,0]
	v_pk_add_f32 v[18:19], v[18:19], v[226:227] op_sel_hi:[1,0]
	v_pk_add_f32 v[20:21], v[20:21], v[226:227] op_sel_hi:[1,0]
	v_pk_add_f32 v[22:23], v[22:23], v[226:227] op_sel_hi:[1,0]
	v_pk_add_f32 v[24:25], v[24:25], v[226:227] op_sel_hi:[1,0]
	v_pk_add_f32 v[26:27], v[26:27], v[226:227] op_sel_hi:[1,0]
	v_pk_add_f32 v[28:29], v[28:29], v[226:227] op_sel_hi:[1,0]
	v_pk_add_f32 v[30:31], v[30:31], v[226:227] op_sel_hi:[1,0]
	v_pk_mul_f32 v[0:1], v[0:1], v[196:197]
	v_pk_mul_f32 v[2:3], v[2:3], v[96:97]
	v_pk_mul_f32 v[4:5], v[4:5], v[134:135]
	v_pk_mul_f32 v[6:7], v[6:7], v[98:99]
	v_pk_mul_f32 v[8:9], v[8:9], v[144:145]
	v_pk_mul_f32 v[10:11], v[10:11], v[118:119]
	v_pk_mul_f32 v[12:13], v[12:13], v[152:153]
	v_pk_mul_f32 v[14:15], v[14:15], v[120:121]
	v_pk_mul_f32 v[16:17], v[16:17], v[156:157]
	v_pk_mul_f32 v[18:19], v[18:19], v[130:131]
	v_pk_mul_f32 v[20:21], v[20:21], v[158:159]
	v_pk_mul_f32 v[22:23], v[22:23], v[122:123]
	v_pk_mul_f32 v[24:25], v[24:25], v[132:133]
	v_pk_mul_f32 v[26:27], v[26:27], v[146:147]
	v_pk_mul_f32 v[28:29], v[28:29], v[166:167]
	v_pk_mul_f32 v[30:31], v[30:31], v[148:149]
	v_pk_mul_f32 v[0:1], v[0:1], v[142:143]
	v_pk_mul_f32 v[2:3], v[2:3], v[92:93]
	v_pk_mul_f32 v[4:5], v[4:5], v[136:137]
	v_pk_mul_f32 v[6:7], v[6:7], v[94:95]
	v_pk_mul_f32 v[8:9], v[8:9], v[150:151]
	v_pk_mul_f32 v[10:11], v[10:11], v[126:127]
	v_pk_mul_f32 v[12:13], v[12:13], v[154:155]
	v_pk_mul_f32 v[14:15], v[14:15], v[128:129]
	v_pk_mul_f32 v[16:17], v[16:17], v[162:163]
	v_pk_mul_f32 v[18:19], v[18:19], v[138:139]
	v_pk_mul_f32 v[20:21], v[20:21], v[160:161]
	v_pk_mul_f32 v[22:23], v[22:23], v[124:125]
	v_pk_mul_f32 v[24:25], v[24:25], v[140:141]
	v_pk_mul_f32 v[26:27], v[26:27], v[164:165]
	v_pk_mul_f32 v[28:29], v[28:29], v[168:169]
	v_pk_mul_f32 v[30:31], v[30:31], v[170:171]
	v_cvt_pk_bf16_f32 v0, v0, v1
	v_cvt_pk_bf16_f32 v1, v2, v3
	v_cvt_pk_bf16_f32 v2, v4, v5
	v_cvt_pk_bf16_f32 v3, v6, v7
	v_cvt_pk_bf16_f32 v4, v8, v9
	v_cvt_pk_bf16_f32 v5, v10, v11
	v_cvt_pk_bf16_f32 v6, v12, v13
	v_cvt_pk_bf16_f32 v7, v14, v15
	v_cvt_pk_bf16_f32 v8, v16, v17
	v_cvt_pk_bf16_f32 v9, v18, v19
	v_cvt_pk_bf16_f32 v10, v20, v21
	v_cvt_pk_bf16_f32 v11, v22, v23
	v_cvt_pk_bf16_f32 v12, v24, v25
	v_cvt_pk_bf16_f32 v13, v26, v27
	v_cvt_pk_bf16_f32 v14, v28, v29
	v_cvt_pk_bf16_f32 v15, v30, v31
	ds_write2_b64 v116, v[0:1], v[2:3] offset1:2
	ds_write2_b64 v116, v[4:5], v[6:7] offset0:4 offset1:6
	ds_write2_b64 v116, v[8:9], v[10:11] offset0:8 offset1:10
	ds_write2_b64 v116, v[12:13], v[14:15] offset0:12 offset1:14
	s_waitcnt lgkmcnt(0)
	s_barrier
	ds_read_b128 v[0:3], v32 offset:34816
	ds_read_b128 v[4:7], v107 offset:34816
	ds_read_b128 v[8:11], v108 offset:34816
	ds_read_b128 v[12:15], v109 offset:34816
	s_waitcnt lgkmcnt(3)
	global_store_dwordx4 v[84:85], v[0:3], off
	s_waitcnt lgkmcnt(2)
	global_store_dwordx4 v[86:87], v[4:7], off
	s_waitcnt lgkmcnt(1)
	global_store_dwordx4 v[88:89], v[8:11], off
	s_waitcnt lgkmcnt(0)
	global_store_dwordx4 v[90:91], v[12:15], off
	s_barrier
	s_cbranch_scc1 .LBB0_456
	s_add_i32 s31, s31, s48
	s_add_i32 s1, s1, s7
	s_cmpk_gt_i32 s31, 0xff
	s_cbranch_scc0 .LBB0_451
